# speedup vs baseline: 1.0068x; 1.0020x over previous
; DI unsigned pk2(float lo, float hi) { const f32x2_t v = {lo, hi}; const bf16x2_t b = __builtin_convertvector(v, bf16x2_t); return __builtin_bit_cast(unsigned, b); }
; DI float lo16(unsigned w) { return __uint_as_float(w << 16); }
; DI float hi16(unsigned w) { return __uint_as_float(w & 0xffff0000u); }
; DI void shortconv_pass(const Args& a, int G, const int tid) {
;     ...
;         for (int tt = 0; tt < len; ++tt) {
;             const int t = t0 + tt; const bf16_t* rp = S + (row0 + t) * 2048; float g0[16];
; #pragma unroll
;             for (int q = 0; q < 2; ++q) { const u32x4 bw4 = *(const u32x4*)(rp + ch + 8 * q), gw4 = *(const u32x4*)(rp + 1024 + ch + 8 * q);
;                 u32x4 ow;
; #pragma unroll
;                 for (int e = 0; e < 4; ++e) { const int i0 = 8 * q + 2 * e; g0[i0] = lo16(gw4[e]); g0[i0 + 1] = hi16(gw4[e]);
;                     const float u0 = w0[i0] * g2[i0] + w1[i0] * g1[i0] + w2[i0] * g0[i0], u1 = w0[i0 + 1] * g2[i0 + 1] + w1[i0 + 1] * g1[i0 + 1] + w2[i0 + 1] * g0[i0 + 1];
;                     ow[e] = pk2(lo16(bw4[e]) * u0, hi16(bw4[e]) * u1); }
;                 *(u32x4*)(V1 + (row0 + t) * 1024 + ch + 8 * q) = ow; }
;             if (t >= L - 2) { float* so = a.out + (sample ? O_SSC : O_PSC) + ((size_t)b * 2 + (t - (L - 2))) * 1024 + ch;
; #pragma unroll
;                 for (int q = 0; q < 4; ++q) *(f32x4*)(so + 4 * q) = (f32x4){g0[4 * q], g0[4 * q + 1], g0[4 * q + 2], g0[4 * q + 3]}; }
; #pragma unroll
;             for (int e = 0; e < 16; ++e) { g2[e] = g1[e]; g1[e] = g0[e]; }
.LBB0_433:
	s_or_b64 exec, exec, s[10:11]
	v_mov_b64_e32 v[64:65], v[216:217]
	v_mov_b64_e32 v[66:67], v[218:219]
	v_mov_b64_e32 v[68:69], v[220:221]
	v_mov_b64_e32 v[70:71], v[222:223]
	v_mov_b64_e32 v[72:73], v[224:225]
	v_mov_b64_e32 v[74:75], v[226:227]
	v_mov_b64_e32 v[80:81], v[232:233]
	v_mov_b64_e32 v[82:83], v[234:235]
	v_add_u32_e32 v119, -1, v119
	v_cmp_eq_u32_e32 vcc, 0, v119
	v_add_u32_e32 v160, 1, v160
	s_or_b64 s[8:9], vcc, s[8:9]
	v_mov_b32_e32 v51, v99
	s_andn2_b64 exec, exec, s[8:9]
	s_cbranch_execz .LBB0_425
.LBB0_434:
	v_mov_b32_e32 v117, v53
	v_mov_b32_e32 v116, v52
	s_waitcnt vmcnt(1)
	v_mov_b32_e32 v53, v65
	v_mov_b32_e32 v52, v64
	v_lshl_add_u64 v[64:65], v[96:97], 0, v[160:161]
	v_mov_b32_e32 v115, v55
	v_mov_b32_e32 v114, v54
	v_mov_b32_e32 v55, v67
	v_mov_b32_e32 v54, v66
	v_lshlrev_b64 v[66:67], 12, v[64:65]
	v_lshl_add_u64 v[66:67], v[94:95], 0, v[66:67]
	v_mov_b32_e32 v50, v98
	v_mov_b32_e32 v103, v49
	v_mov_b32_e32 v102, v48
	v_mov_b32_e32 v109, v61
	v_mov_b32_e32 v108, v60
	v_mov_b32_e32 v111, v59
	v_mov_b32_e32 v110, v58
	s_waitcnt vmcnt(0)
	v_mov_b32_e32 v99, v83
	v_mov_b32_e32 v98, v82
	v_mov_b32_e32 v49, v81
	v_mov_b32_e32 v48, v80
	v_mov_b32_e32 v61, v73
	v_mov_b32_e32 v60, v72
	v_mov_b32_e32 v59, v71
	v_mov_b32_e32 v58, v70
	global_load_dwordx4 v[76:79], v[66:67], off offset:16
	global_load_dwordx4 v[70:73], v[66:67], off
	global_load_dwordx4 v[80:83], v[66:67], off offset:2064
	global_load_dwordx4 v[84:87], v[66:67], off offset:2048
	v_add_co_u32_e32 v218, vcc, 0x1000, v66
	s_nop 1
	v_addc_co_u32_e32 v219, vcc, 0, v67, vcc
	global_load_dwordx4 v[228:231], v[218:219], off offset:16
	global_load_dwordx4 v[222:225], v[218:219], off
	global_load_dwordx4 v[232:235], v[218:219], off offset:2064
	global_load_dwordx4 v[236:239], v[218:219], off offset:2048
	v_lshlrev_b64 v[64:65], 11, v[64:65]
	v_pk_mul_f32 v[66:67], v[24:25], v[52:53]
	v_lshl_add_u64 v[106:107], v[90:91], 0, v[64:65]
	v_pk_fma_f32 v[66:67], v[8:9], v[116:117], v[66:67]
	v_mov_b32_e32 v113, v57
	v_mov_b32_e32 v112, v56
	v_mov_b32_e32 v57, v69
	v_mov_b32_e32 v56, v68
	v_mov_b32_e32 v105, v63
	v_mov_b32_e32 v104, v62
	v_mov_b32_e32 v63, v75
	v_mov_b32_e32 v62, v74
	v_cmp_ge_u32_e32 vcc, v160, v118
	s_waitcnt vmcnt(6)
	v_lshlrev_b32_e32 v68, 16, v70
	v_and_b32_e32 v69, 0xffff0000, v70
	s_waitcnt vmcnt(4)
	v_lshlrev_b32_e32 v64, 16, v84
	v_and_b32_e32 v65, 0xffff0000, v84
	v_pk_fma_f32 v[66:67], v[28:29], v[64:65], v[66:67]
	v_lshlrev_b32_e32 v70, 16, v71
	v_pk_mul_f32 v[66:67], v[66:67], v[68:69]
	v_pk_mul_f32 v[68:69], v[26:27], v[54:55]
	v_cvt_pk_bf16_f32 v84, v66, v67
	v_lshlrev_b32_e32 v66, 16, v85
	v_and_b32_e32 v67, 0xffff0000, v85
	v_pk_fma_f32 v[68:69], v[10:11], v[114:115], v[68:69]
	v_and_b32_e32 v71, 0xffff0000, v71
	v_pk_fma_f32 v[68:69], v[30:31], v[66:67], v[68:69]
	v_lshlrev_b32_e32 v74, 16, v72
	v_pk_mul_f32 v[68:69], v[68:69], v[70:71]
	v_pk_mul_f32 v[70:71], v[20:21], v[56:57]
	v_cvt_pk_bf16_f32 v85, v68, v69
	v_lshlrev_b32_e32 v68, 16, v86
	v_and_b32_e32 v69, 0xffff0000, v86
	v_pk_fma_f32 v[70:71], v[12:13], v[112:113], v[70:71]
	v_and_b32_e32 v75, 0xffff0000, v72
	v_pk_fma_f32 v[70:71], v[44:45], v[68:69], v[70:71]
	v_lshlrev_b32_e32 v72, 16, v73
	v_pk_mul_f32 v[70:71], v[70:71], v[74:75]
	v_pk_mul_f32 v[74:75], v[22:23], v[58:59]
	v_cvt_pk_bf16_f32 v86, v70, v71
	v_lshlrev_b32_e32 v70, 16, v87
	v_and_b32_e32 v71, 0xffff0000, v87
	v_pk_fma_f32 v[74:75], v[14:15], v[110:111], v[74:75]
	v_and_b32_e32 v73, 0xffff0000, v73
	v_pk_fma_f32 v[74:75], v[46:47], v[70:71], v[74:75]
	v_pk_mul_f32 v[72:73], v[74:75], v[72:73]
	v_pk_mul_f32 v[74:75], v[16:17], v[60:61]
	v_cvt_pk_bf16_f32 v87, v72, v73
	v_lshlrev_b32_e32 v72, 16, v80
	v_and_b32_e32 v73, 0xffff0000, v80
	v_pk_fma_f32 v[74:75], v[0:1], v[108:109], v[74:75]
	global_store_dwordx4 v[106:107], v[84:87], off
	v_pk_fma_f32 v[74:75], v[32:33], v[72:73], v[74:75]
	s_nop 0
	v_lshlrev_b32_e32 v84, 16, v76
	v_and_b32_e32 v85, 0xffff0000, v76
	v_pk_mul_f32 v[74:75], v[74:75], v[84:85]
	v_lshlrev_b32_e32 v84, 16, v77
	v_cvt_pk_bf16_f32 v76, v74, v75
	v_lshlrev_b32_e32 v74, 16, v81
	v_and_b32_e32 v75, 0xffff0000, v81
	v_pk_mul_f32 v[80:81], v[18:19], v[62:63]
	v_and_b32_e32 v85, 0xffff0000, v77
	v_pk_fma_f32 v[80:81], v[2:3], v[104:105], v[80:81]
	v_lshlrev_b32_e32 v86, 16, v78
	v_pk_fma_f32 v[80:81], v[34:35], v[74:75], v[80:81]
	v_and_b32_e32 v87, 0xffff0000, v78
	v_pk_mul_f32 v[80:81], v[80:81], v[84:85]
	v_pk_mul_f32 v[84:85], v[40:41], v[48:49]
	v_cvt_pk_bf16_f32 v77, v80, v81
	v_lshlrev_b32_e32 v80, 16, v82
	v_and_b32_e32 v81, 0xffff0000, v82
	v_pk_fma_f32 v[84:85], v[4:5], v[102:103], v[84:85]
	v_lshlrev_b32_e32 v82, 16, v83
	v_pk_fma_f32 v[84:85], v[36:37], v[80:81], v[84:85]
	v_and_b32_e32 v83, 0xffff0000, v83
	v_pk_mul_f32 v[84:85], v[84:85], v[86:87]
	v_cvt_pk_bf16_f32 v78, v84, v85
	v_pk_mul_f32 v[84:85], v[42:43], v[98:99]
	v_pk_fma_f32 v[50:51], v[6:7], v[50:51], v[84:85]
	v_lshlrev_b32_e32 v84, 16, v79
	v_pk_fma_f32 v[50:51], v[38:39], v[82:83], v[50:51]
	v_and_b32_e32 v85, 0xffff0000, v79
	v_pk_mul_f32 v[50:51], v[50:51], v[84:85]
	v_cvt_pk_bf16_f32 v79, v50, v51
	global_store_dwordx4 v[106:107], v[76:79], off offset:16
	s_and_saveexec_b64 s[10:11], vcc
	s_cbranch_execz .Lmy_sc_mid
	v_add_u32_e32 v50, v120, v160
	v_mov_b32_e32 v51, v161
	v_lshlrev_b64 v[50:51], 12, v[50:51]
	v_lshl_add_u64 v[50:51], v[100:101], 0, v[50:51]
	global_store_dwordx4 v[50:51], v[64:67], off
	global_store_dwordx4 v[50:51], v[68:71], off offset:16
	global_store_dwordx4 v[50:51], v[72:75], off offset:32
	global_store_dwordx4 v[50:51], v[80:83], off offset:48
	s_branch .Lmy_sc_mid
; DI unsigned pk2(float lo, float hi) { const f32x2_t v = {lo, hi}; const bf16x2_t b = __builtin_convertvector(v, bf16x2_t); return __builtin_bit_cast(unsigned, b); }
; DI float lo16(unsigned w) { return __uint_as_float(w << 16); }
; DI float hi16(unsigned w) { return __uint_as_float(w & 0xffff0000u); }
; DI void shortconv_pass(const Args& a, int G, const int tid) {
;     ...
;         for (int tt = 0; tt < len; ++tt) {
;             const int t = t0 + tt; const bf16_t* rp = S + (row0 + t) * 2048; float g0[16];
; #pragma unroll
;             for (int q = 0; q < 2; ++q) { const u32x4 bw4 = *(const u32x4*)(rp + ch + 8 * q), gw4 = *(const u32x4*)(rp + 1024 + ch + 8 * q);
;                 u32x4 ow;
; #pragma unroll
;                 for (int e = 0; e < 4; ++e) { const int i0 = 8 * q + 2 * e; g0[i0] = lo16(gw4[e]); g0[i0 + 1] = hi16(gw4[e]);
;                     const float u0 = w0[i0] * g2[i0] + w1[i0] * g1[i0] + w2[i0] * g0[i0], u1 = w0[i0 + 1] * g2[i0 + 1] + w1[i0 + 1] * g1[i0 + 1] + w2[i0 + 1] * g0[i0 + 1];
;                     ow[e] = pk2(lo16(bw4[e]) * u0, hi16(bw4[e]) * u1); }
;                 *(u32x4*)(V1 + (row0 + t) * 1024 + ch + 8 * q) = ow; }
;             if (t >= L - 2) { float* so = a.out + (sample ? O_SSC : O_PSC) + ((size_t)b * 2 + (t - (L - 2))) * 1024 + ch;
; #pragma unroll
;                 for (int q = 0; q < 4; ++q) *(f32x4*)(so + 4 * q) = (f32x4){g0[4 * q], g0[4 * q + 1], g0[4 * q + 2], g0[4 * q + 3]}; }
; #pragma unroll
;             for (int e = 0; e < 16; ++e) { g2[e] = g1[e]; g1[e] = g0[e]; }
.Lmy_sc_mid:
	s_or_b64 exec, exec, s[10:11]
	v_add_u32_e32 v119, -1, v119
	v_add_u32_e32 v160, 1, v160
	v_mov_b32_e32 v51, v99
	v_mov_b32_e32 v117, v53
	v_mov_b32_e32 v116, v52
	v_mov_b32_e32 v53, v65
	v_mov_b32_e32 v52, v64
	v_lshl_add_u64 v[216:217], v[96:97], 0, v[160:161]
	v_mov_b32_e32 v115, v55
	v_mov_b32_e32 v114, v54
	v_mov_b32_e32 v55, v67
	v_mov_b32_e32 v54, v66
	v_lshlrev_b64 v[218:219], 12, v[216:217]
	v_lshl_add_u64 v[218:219], v[94:95], 0, v[218:219]
	v_mov_b32_e32 v50, v98
	v_mov_b32_e32 v103, v49
	v_mov_b32_e32 v102, v48
	v_mov_b32_e32 v109, v61
	v_mov_b32_e32 v108, v60
	v_mov_b32_e32 v111, v59
	v_mov_b32_e32 v110, v58
	v_mov_b32_e32 v99, v83
	v_mov_b32_e32 v98, v82
	v_mov_b32_e32 v49, v81
	v_mov_b32_e32 v48, v80
	v_mov_b32_e32 v61, v73
	v_mov_b32_e32 v60, v72
	v_mov_b32_e32 v59, v71
	v_mov_b32_e32 v58, v70
	v_lshlrev_b64 v[216:217], 11, v[216:217]
	v_pk_mul_f32 v[218:219], v[24:25], v[52:53]
	v_lshl_add_u64 v[106:107], v[90:91], 0, v[216:217]
	v_pk_fma_f32 v[218:219], v[8:9], v[116:117], v[218:219]
	v_mov_b32_e32 v113, v57
	v_mov_b32_e32 v112, v56
	v_mov_b32_e32 v57, v69
	v_mov_b32_e32 v56, v68
	v_mov_b32_e32 v105, v63
	v_mov_b32_e32 v104, v62
	v_mov_b32_e32 v63, v75
	v_mov_b32_e32 v62, v74
	v_cmp_ge_u32_e32 vcc, v160, v118
	s_waitcnt vmcnt(2)
	v_lshlrev_b32_e32 v220, 16, v222
	v_and_b32_e32 v221, 0xffff0000, v222
	s_waitcnt vmcnt(2)
	v_lshlrev_b32_e32 v216, 16, v236
	v_and_b32_e32 v217, 0xffff0000, v236
	v_pk_fma_f32 v[218:219], v[28:29], v[216:217], v[218:219]
	v_lshlrev_b32_e32 v222, 16, v223
	v_pk_mul_f32 v[218:219], v[218:219], v[220:221]
	v_pk_mul_f32 v[220:221], v[26:27], v[54:55]
	v_cvt_pk_bf16_f32 v236, v218, v219
	v_lshlrev_b32_e32 v218, 16, v237
	v_and_b32_e32 v219, 0xffff0000, v237
	v_pk_fma_f32 v[220:221], v[10:11], v[114:115], v[220:221]
	v_and_b32_e32 v223, 0xffff0000, v223
	v_pk_fma_f32 v[220:221], v[30:31], v[218:219], v[220:221]
	v_lshlrev_b32_e32 v226, 16, v224
	v_pk_mul_f32 v[220:221], v[220:221], v[222:223]
	v_pk_mul_f32 v[222:223], v[20:21], v[56:57]
	v_cvt_pk_bf16_f32 v237, v220, v221
	v_lshlrev_b32_e32 v220, 16, v238
	v_and_b32_e32 v221, 0xffff0000, v238
	v_pk_fma_f32 v[222:223], v[12:13], v[112:113], v[222:223]
	v_and_b32_e32 v227, 0xffff0000, v224
	v_pk_fma_f32 v[222:223], v[44:45], v[220:221], v[222:223]
	v_lshlrev_b32_e32 v224, 16, v225
	v_pk_mul_f32 v[222:223], v[222:223], v[226:227]
	v_pk_mul_f32 v[226:227], v[22:23], v[58:59]
	v_cvt_pk_bf16_f32 v238, v222, v223
	v_lshlrev_b32_e32 v222, 16, v239
	v_and_b32_e32 v223, 0xffff0000, v239
	v_pk_fma_f32 v[226:227], v[14:15], v[110:111], v[226:227]
	v_and_b32_e32 v225, 0xffff0000, v225
	v_pk_fma_f32 v[226:227], v[46:47], v[222:223], v[226:227]
	v_pk_mul_f32 v[224:225], v[226:227], v[224:225]
	v_pk_mul_f32 v[226:227], v[16:17], v[60:61]
	v_cvt_pk_bf16_f32 v239, v224, v225
	v_lshlrev_b32_e32 v224, 16, v232
	v_and_b32_e32 v225, 0xffff0000, v232
	v_pk_fma_f32 v[226:227], v[0:1], v[108:109], v[226:227]
	global_store_dwordx4 v[106:107], v[236:239], off
	v_pk_fma_f32 v[226:227], v[32:33], v[224:225], v[226:227]
	s_nop 0
	v_lshlrev_b32_e32 v236, 16, v228
	v_and_b32_e32 v237, 0xffff0000, v228
	v_pk_mul_f32 v[226:227], v[226:227], v[236:237]
	v_lshlrev_b32_e32 v236, 16, v229
	v_cvt_pk_bf16_f32 v228, v226, v227
	v_lshlrev_b32_e32 v226, 16, v233
	v_and_b32_e32 v227, 0xffff0000, v233
	v_pk_mul_f32 v[232:233], v[18:19], v[62:63]
	v_and_b32_e32 v237, 0xffff0000, v229
	v_pk_fma_f32 v[232:233], v[2:3], v[104:105], v[232:233]
	v_lshlrev_b32_e32 v238, 16, v230
	v_pk_fma_f32 v[232:233], v[34:35], v[226:227], v[232:233]
	v_and_b32_e32 v239, 0xffff0000, v230
	v_pk_mul_f32 v[232:233], v[232:233], v[236:237]
	v_pk_mul_f32 v[236:237], v[40:41], v[48:49]
	v_cvt_pk_bf16_f32 v229, v232, v233
	v_lshlrev_b32_e32 v232, 16, v234
	v_and_b32_e32 v233, 0xffff0000, v234
	v_pk_fma_f32 v[236:237], v[4:5], v[102:103], v[236:237]
	v_lshlrev_b32_e32 v234, 16, v235
	v_pk_fma_f32 v[236:237], v[36:37], v[232:233], v[236:237]
	v_and_b32_e32 v235, 0xffff0000, v235
	v_pk_mul_f32 v[236:237], v[236:237], v[238:239]
	v_cvt_pk_bf16_f32 v230, v236, v237
	v_pk_mul_f32 v[236:237], v[42:43], v[98:99]
	v_pk_fma_f32 v[50:51], v[6:7], v[50:51], v[236:237]
	v_lshlrev_b32_e32 v236, 16, v231
	v_pk_fma_f32 v[50:51], v[38:39], v[234:235], v[50:51]
	v_and_b32_e32 v237, 0xffff0000, v231
	v_pk_mul_f32 v[50:51], v[50:51], v[236:237]
	v_cvt_pk_bf16_f32 v231, v50, v51
	global_store_dwordx4 v[106:107], v[228:231], off offset:16
	s_and_saveexec_b64 s[10:11], vcc
	s_cbranch_execz .LBB0_433
	v_add_u32_e32 v50, v120, v160
	v_mov_b32_e32 v51, v161
	v_lshlrev_b64 v[50:51], 12, v[50:51]
	v_lshl_add_u64 v[50:51], v[100:101], 0, v[50:51]
	global_store_dwordx4 v[50:51], v[216:219], off
	global_store_dwordx4 v[50:51], v[220:223], off offset:16
	global_store_dwordx4 v[50:51], v[224:227], off offset:32
	global_store_dwordx4 v[50:51], v[232:235], off offset:48
	s_branch .LBB0_433
